# speedup vs baseline: 1.0341x; 1.0088x over previous
; __device__ __forceinline__ void sb_wave(int b, int h, int qw0, int kt_lo, const bf16x8_t (&qr)[4], const bf16_t* __restrict__ K, const bf16_t* __restrict__ V, bf16_t* O, LAS unsigned char* lds, int wave, int lane) {
;     ...
;         f32x16_t st = {};
; #pragma unroll
;         for (int d0 = 0; d0 < 4; ++d0) st = __builtin_amdgcn_mfma_f32_32x32x16_bf16(kf[d0], qr[d0], st, 0, 0, 0);
;         float l1[16], lb[16]; bool val[16];
; #pragma unroll
;         for (int r = 0; r < 16; ++r) { const int kv = kt * 32 + (r & 3) + 8 * (r >> 2) + 4 * hi; val[r] = kv < qabs; const float z = st[r] * (0.125f * LOG2E); const float sp = fmaxf(z, 0.f) + __builtin_amdgcn_logf(1.f + __builtin_amdgcn_exp2f(-fabsf(z))); l1[r] = val[r] ? -sp : 0.f; lb[r] = z - sp; }
;         float w[16]; float tail = 0.f;
; #pragma unroll
;         for (int g = 3; g >= 0; --g) { const float qs = (l1[4 * g] + l1[4 * g + 1]) + (l1[4 * g + 2] + l1[4 * g + 3]); const float pq = __shfl_xor(qs, 32);
;             const float after = tail + (hi == 0 ? pq : 0.f) + R; tail += qs + pq;
;             const float e2 = l1[4 * g + 3], e1 = e2 + l1[4 * g + 2], e0 = e1 + l1[4 * g + 1];
.LBB9_574:
	s_waitcnt lgkmcnt(3)
	v_mfma_f32_32x32x16_bf16 v[34:49], v[34:37], v[50:53], 0
	v_or_b32_e32 v0, s67, v110
	v_cmp_lt_i32_e32 vcc, v0, v138
	v_add_u32_e32 v141, 0xffffee00, v141
	s_waitcnt lgkmcnt(2)
	v_mfma_f32_32x32x16_bf16 v[34:49], v[66:69], v[54:57], v[34:49]
	s_waitcnt lgkmcnt(1)
	v_mfma_f32_32x32x16_bf16 v[34:49], v[70:73], v[58:61], v[34:49]
	s_waitcnt lgkmcnt(0)
	v_mfma_f32_32x32x16_bf16 v[34:49], v[74:77], v[62:65], v[34:49]
	s_nop 11
	v_mul_f32_e32 v66, 0x3e38aa3b, v34
	v_max_f32_e32 v67, 0, v66
	v_exp_f32_e64 v66, -|v66|
	s_nop 0
	v_add_f32_e32 v66, 1.0, v66
	v_log_f32_e32 v66, v66
	s_nop 0
	v_add_f32_e32 v66, v67, v66
	v_fma_f32 v67, v34, s89, -v66
	v_or_b32_e32 v34, 1, v0
	v_cmp_lt_i32_e64 s[8:9], v34, v138
	v_mul_f32_e32 v34, 0x3e38aa3b, v35
	v_cndmask_b32_e64 v69, 0, -v66, vcc
	v_max_f32_e32 v66, 0, v34
	v_exp_f32_e64 v34, -|v34|
	s_nop 0
	v_add_f32_e32 v34, 1.0, v34
	v_log_f32_e32 v34, v34
	s_nop 0
	v_add_f32_e32 v34, v66, v34
	v_cndmask_b32_e64 v66, 0, -v34, s[8:9]
	v_fma_f32 v68, v35, s89, -v34
	v_or_b32_e32 v34, 2, v0
	v_cmp_lt_i32_e64 s[10:11], v34, v138
	v_mul_f32_e32 v34, 0x3e38aa3b, v36
	v_max_f32_e32 v35, 0, v34
	v_exp_f32_e64 v34, -|v34|
	s_nop 0
	v_add_f32_e32 v34, 1.0, v34
	v_log_f32_e32 v34, v34
	s_nop 0
	v_add_f32_e32 v34, v35, v34
	v_cndmask_b32_e64 v71, 0, -v34, s[10:11]
	v_fma_f32 v70, v36, s89, -v34
	v_or_b32_e32 v34, 3, v0
	v_cmp_lt_i32_e64 s[12:13], v34, v138
	v_mul_f32_e32 v34, 0x3e38aa3b, v37
	v_max_f32_e32 v35, 0, v34
	v_exp_f32_e64 v34, -|v34|
	s_nop 0
	v_add_f32_e32 v34, 1.0, v34
	v_log_f32_e32 v34, v34
	s_nop 0
	v_add_f32_e32 v34, v35, v34
	v_cndmask_b32_e64 v72, 0, -v34, s[12:13]
	v_fma_f32 v73, v37, s89, -v34
	v_or_b32_e32 v34, 8, v0
	v_cmp_lt_i32_e64 s[14:15], v34, v138
	v_mul_f32_e32 v34, 0x3e38aa3b, v38
	v_max_f32_e32 v35, 0, v34
	v_exp_f32_e64 v34, -|v34|
	s_nop 0
	v_add_f32_e32 v34, 1.0, v34
	v_log_f32_e32 v34, v34
	s_nop 0
	v_add_f32_e32 v34, v35, v34
	v_cndmask_b32_e64 v74, 0, -v34, s[14:15]
	v_fma_f32 v35, v38, s89, -v34
	v_or_b32_e32 v34, 9, v0
	v_cmp_lt_i32_e64 s[16:17], v34, v138
	v_mul_f32_e32 v34, 0x3e38aa3b, v39
	v_max_f32_e32 v36, 0, v34
	v_exp_f32_e64 v34, -|v34|
	s_nop 0
	v_add_f32_e32 v34, 1.0, v34
	v_log_f32_e32 v34, v34
	s_nop 0
	v_add_f32_e32 v36, v36, v34
	v_cndmask_b32_e64 v34, 0, -v36, s[16:17]
	v_fma_f32 v75, v39, s89, -v36
	v_or_b32_e32 v36, 10, v0
	v_cmp_lt_i32_e64 s[18:19], v36, v138
	v_mul_f32_e32 v36, 0x3e38aa3b, v40
	v_max_f32_e32 v37, 0, v36
	v_exp_f32_e64 v36, -|v36|
	s_nop 0
	v_add_f32_e32 v36, 1.0, v36
	v_log_f32_e32 v36, v36
	s_nop 0
	v_add_f32_e32 v36, v37, v36
	v_cndmask_b32_e64 v76, 0, -v36, s[18:19]
	v_fma_f32 v40, v40, s89, -v36
	v_or_b32_e32 v36, 11, v0
	v_cmp_lt_i32_e64 s[20:21], v36, v138
	v_mul_f32_e32 v36, 0x3e38aa3b, v41
	v_max_f32_e32 v37, 0, v36
	v_exp_f32_e64 v36, -|v36|
	s_nop 0
	v_add_f32_e32 v36, 1.0, v36
	v_log_f32_e32 v36, v36
	s_nop 0
	v_add_f32_e32 v36, v37, v36
	v_cndmask_b32_e64 v77, 0, -v36, s[20:21]
	v_fma_f32 v41, v41, s89, -v36
	v_or_b32_e32 v36, 16, v0
	v_cmp_lt_i32_e64 s[22:23], v36, v138
	v_mul_f32_e32 v36, 0x3e38aa3b, v42
	v_max_f32_e32 v37, 0, v36
	v_exp_f32_e64 v36, -|v36|
	s_nop 0
	v_add_f32_e32 v36, 1.0, v36
	v_log_f32_e32 v36, v36
	s_nop 0
	v_add_f32_e32 v36, v37, v36
	v_cndmask_b32_e64 v38, 0, -v36, s[22:23]
	v_fma_f32 v42, v42, s89, -v36
	v_or_b32_e32 v36, 17, v0
	v_cmp_lt_i32_e64 s[24:25], v36, v138
	v_mul_f32_e32 v36, 0x3e38aa3b, v43
	v_max_f32_e32 v37, 0, v36
	v_exp_f32_e64 v36, -|v36|
	s_nop 0
	v_add_f32_e32 v36, 1.0, v36
	v_log_f32_e32 v36, v36
	s_nop 0
	v_add_f32_e32 v37, v37, v36
	v_cndmask_b32_e64 v36, 0, -v37, s[24:25]
	v_fma_f32 v43, v43, s89, -v37
	v_or_b32_e32 v37, 18, v0
	v_cmp_lt_i32_e64 s[26:27], v37, v138
	v_mul_f32_e32 v37, 0x3e38aa3b, v44
	v_max_f32_e32 v39, 0, v37
	v_exp_f32_e64 v37, -|v37|
	s_nop 0
	v_add_f32_e32 v37, 1.0, v37
	v_log_f32_e32 v37, v37
	s_nop 0
	v_add_f32_e32 v37, v39, v37
	v_cndmask_b32_e64 v147, 0, -v37, s[26:27]
	v_fma_f32 v148, v44, s89, -v37
	v_or_b32_e32 v37, 19, v0
	v_cmp_lt_i32_e64 s[28:29], v37, v138
	v_mul_f32_e32 v37, 0x3e38aa3b, v45
	v_max_f32_e32 v39, 0, v37
	v_exp_f32_e64 v37, -|v37|
	s_nop 0
	v_add_f32_e32 v37, 1.0, v37
	v_log_f32_e32 v37, v37
	s_nop 0
	v_add_f32_e32 v37, v39, v37
	v_cndmask_b32_e64 v149, 0, -v37, s[28:29]
	v_fma_f32 v150, v45, s89, -v37
	v_or_b32_e32 v37, 24, v0
	v_cmp_lt_i32_e64 s[30:31], v37, v138
	v_mul_f32_e32 v37, 0x3e38aa3b, v46
	v_max_f32_e32 v39, 0, v37
	v_exp_f32_e64 v37, -|v37|
	s_nop 0
	v_add_f32_e32 v37, 1.0, v37
	v_log_f32_e32 v37, v37
	s_nop 0
	v_add_f32_e32 v37, v39, v37
	v_cndmask_b32_e64 v39, 0, -v37, s[30:31]
	v_fma_f32 v44, v46, s89, -v37
	v_or_b32_e32 v37, 25, v0
	v_cmp_lt_i32_e64 s[34:35], v37, v138
	v_mul_f32_e32 v37, 0x3e38aa3b, v47
	v_max_f32_e32 v45, 0, v37
	v_exp_f32_e64 v37, -|v37|
	s_nop 0
	v_add_f32_e32 v37, 1.0, v37
	v_log_f32_e32 v37, v37
	s_nop 0
	v_add_f32_e32 v37, v45, v37
	v_cndmask_b32_e64 v45, 0, -v37, s[34:35]
	v_fma_f32 v151, v47, s89, -v37
	v_or_b32_e32 v37, 26, v0
	v_cmp_lt_i32_e64 s[36:37], v37, v138
	v_mul_f32_e32 v37, 0x3e38aa3b, v48
	v_max_f32_e32 v46, 0, v37
	v_exp_f32_e64 v37, -|v37|
	v_or_b32_e32 v0, 27, v0
	v_cmp_lt_i32_e64 s[38:39], v0, v138
	v_mul_f32_e32 v0, 0x3e38aa3b, v49
	v_add_f32_e32 v37, 1.0, v37
	v_log_f32_e32 v37, v37
	v_add_f32_e32 v39, v39, v45
	v_add_f32_e32 v37, v46, v37
	v_cndmask_b32_e64 v46, 0, -v37, s[36:37]
	v_fma_f32 v152, v48, s89, -v37
	v_max_f32_e32 v37, 0, v0
	v_exp_f32_e64 v0, -|v0|
	s_nop 0
	v_add_f32_e32 v0, 1.0, v0
	v_log_f32_e32 v0, v0
	s_nop 0
	v_add_f32_e32 v0, v37, v0
	v_cndmask_b32_e64 v153, 0, -v0, s[38:39]
	v_add_f32_e32 v37, v46, v153
	v_pk_add_f32 v[38:39], v[38:39], v[36:37]
	ds_bpermute_b32 v47, v140, v39
	v_fma_f32 v0, v49, s89, -v0
	v_add_f32_e32 v46, v147, v149
	v_mov_b32_e32 v49, v37
	s_waitcnt lgkmcnt(0)
; __device__ __forceinline__ unsigned cvtpk_s(float lo,float hi){f32x2_t v={lo,hi};bf16x2_t b=__builtin_convertvector(v,bf16x2_t);return __builtin_bit_cast(unsigned,b);}
; #define SB_VF(d0, s) ({ const attn_body::s16x4 lo_ = attn_body::vtr(vp + (d0) * 2048 + (s) * 1024), hi_ = attn_body::vtr(vp + (d0) * 2048 + (s) * 1024 + 512); \
;             (bf16x8_t){lo_[0], lo_[1], lo_[2], lo_[3], hi_[0], hi_[1], hi_[2], hi_[3]}; })
; __device__ __forceinline__ void sb_wave(int b, int h, int qw0, int kt_lo, const bf16x8_t (&qr)[4], const bf16_t* __restrict__ K, const bf16_t* __restrict__ V, bf16_t* O, LAS unsigned char* lds, int wave, int lane) {
;     ...
;         for (int g = 3; g >= 0; --g) { const float qs = (l1[4 * g] + l1[4 * g + 1]) + (l1[4 * g + 2] + l1[4 * g + 3]); const float pq = __shfl_xor(qs, 32);
;             const float after = tail + (hi == 0 ? pq : 0.f) + R; tail += qs + pq;
;             const float e2 = l1[4 * g + 3], e1 = e2 + l1[4 * g + 2], e0 = e1 + l1[4 * g + 1];
;             w[4 * g + 3] = val[4 * g + 3] ? __builtin_amdgcn_exp2f(lb[4 * g + 3] + after) : 0.f; w[4 * g + 2] = val[4 * g + 2] ? __builtin_amdgcn_exp2f(lb[4 * g + 2] + after + e2) : 0.f;
;             w[4 * g + 1] = val[4 * g + 1] ? __builtin_amdgcn_exp2f(lb[4 * g + 1] + after + e1) : 0.f; w[4 * g] = val[4 * g] ? __builtin_amdgcn_exp2f(lb[4 * g] + after + e0) : 0.f; }
;         R += tail;
;         u32x4 p0, p1; p0.x = attn_body::cvtpk_s(w[0], w[1]); p0.y = attn_body::cvtpk_s(w[2], w[3]); p0.z = attn_body::cvtpk_s(w[4], w[5]); p0.w = attn_body::cvtpk_s(w[6], w[7]);
;         p1.x = attn_body::cvtpk_s(w[8], w[9]); p1.y = attn_body::cvtpk_s(w[10], w[11]); p1.z = attn_body::cvtpk_s(w[12], w[13]); p1.w = attn_body::cvtpk_s(w[14], w[15]);
;         const bf16x8_t pa0 = __builtin_bit_cast(bf16x8_t, p0), pa1 = __builtin_bit_cast(bf16x8_t, p1);
;         const attn_body::lds_cptr vp = (attn_body::lds_cptr)vl + (4 * hi + ((lane & 15) >> 2)) * 64 + ((lane >> 4) & 1) * 32 + (lane & 3) * 8;
;     ...
;         o0 = __builtin_amdgcn_mfma_f32_32x32x16_bf16(pa0, SB_VF(0, 0), o0, 0, 0, 0);
;         o1 = __builtin_amdgcn_mfma_f32_32x32x16_bf16(pa0, SB_VF(1, 0), o1, 0, 0, 0);
;         o0 = __builtin_amdgcn_mfma_f32_32x32x16_bf16(pa1, SB_VF(0, 1), o0, 0, 0, 0);
;         o1 = __builtin_amdgcn_mfma_f32_32x32x16_bf16(pa1, SB_VF(1, 1), o1, 0, 0, 0);
;     ...
;         if (__all(R < SB_THR * LOG2E)) break;
	v_add_f32_e32 v48, 0, v47
	v_cndmask_b32_e64 v48, 0, v48, s[6:7]
	v_add_f32_e32 v48, v142, v48
	v_add_f32_e32 v0, v48, v0
	v_exp_f32_e32 v0, v0
	v_pk_add_f32 v[44:45], v[44:45], v[48:49]
	v_pk_add_f32 v[38:39], v[38:39], v[46:47]
	v_cndmask_b32_e64 v147, 0, v0, s[38:39]
	v_add_f32_e32 v0, v48, v152
	v_add_f32_e32 v0, v153, v0
	v_exp_f32_e32 v0, v0
	s_nop 0
	v_cndmask_b32_e64 v152, 0, v0, s[36:37]
	v_add_f32_e32 v0, v48, v151
	v_add_f32_e32 v0, v37, v0
	v_exp_f32_e32 v0, v0
	s_nop 0
	v_cndmask_b32_e64 v151, 0, v0, s[34:35]
	v_add_f32_e32 v0, v44, v45
	v_exp_f32_e32 v0, v0
	s_nop 0
	v_cndmask_b32_e64 v48, 0, v0, s[30:31]
	ds_bpermute_b32 v0, v140, v38
	s_waitcnt lgkmcnt(0)
	v_cndmask_b32_e64 v37, 0, v0, s[6:7]
	v_pk_add_f32 v[38:39], v[38:39], v[0:1]
	s_nop 0
	v_add_f32_e32 v0, v37, v39
	v_add_f32_e32 v47, v142, v0
	v_add_f32_e32 v37, v148, v47
	v_add_f32_e32 v37, v149, v37
	v_exp_f32_e32 v37, v37
	v_mov_b32_e32 v45, v39
	v_add_f32_e32 v0, v150, v47
	v_exp_f32_e32 v0, v0
	v_cndmask_b32_e64 v49, 0, v37, s[26:27]
	v_add_f32_e32 v37, v43, v47
	v_add_f32_e32 v37, v46, v37
	v_exp_f32_e32 v37, v37
	v_mov_b32_e32 v43, v38
	v_cndmask_b32_e64 v0, 0, v0, s[28:29]
	v_cndmask_b32_e64 v148, 0, v37, s[24:25]
	v_mov_b32_e32 v37, v42
	v_pk_add_f32 v[36:37], v[36:37], v[46:47]
	s_nop 0
	v_add_f32_e32 v36, v36, v37
	v_exp_f32_e32 v36, v36
	v_add_f32_e32 v37, v74, v34
	v_cndmask_b32_e64 v46, 0, v36, s[22:23]
	v_add_f32_e32 v36, v76, v77
	v_add_f32_e32 v42, v37, v36
	ds_bpermute_b32 v44, v140, v42
	s_waitcnt lgkmcnt(0)
	v_cndmask_b32_e64 v37, 0, v44, s[6:7]
	v_pk_add_f32 v[38:39], v[42:43], v[44:45]
	s_nop 0
	v_add_f32_e32 v37, v37, v39
	v_add_f32_e32 v37, v142, v37
	v_add_f32_e32 v40, v40, v37
	v_add_f32_e32 v40, v77, v40
	v_exp_f32_e32 v40, v40
	v_pk_add_f32 v[34:35], v[34:35], v[36:37]
	v_add_f32_e32 v41, v41, v37
	v_add_f32_e32 v34, v34, v35
	v_cndmask_b32_e64 v43, 0, v40, s[18:19]
	v_add_f32_e32 v40, v75, v37
	v_exp_f32_e32 v34, v34
	v_add_f32_e32 v40, v36, v40
	v_exp_f32_e32 v40, v40
	v_add_f32_e32 v35, v69, v66
	v_cndmask_b32_e64 v45, 0, v34, s[14:15]
	v_add_f32_e32 v34, v71, v72
	v_add_f32_e32 v36, v35, v34
	v_exp_f32_e32 v41, v41
	v_cndmask_b32_e64 v44, 0, v40, s[16:17]
	ds_bpermute_b32 v40, v140, v36
	v_mov_b32_e32 v37, v38
	v_cndmask_b32_e64 v42, 0, v41, s[20:21]
	v_mov_b32_e32 v41, v39
	s_waitcnt lgkmcnt(0)
	v_cndmask_b32_e64 v35, 0, v40, s[6:7]
	v_pk_add_f32 v[36:37], v[36:37], v[40:41]
	v_cvt_pk_bf16_f32 v40, v48, v151
	v_add_f32_e32 v35, v35, v37
	v_add_f32_e32 v35, v142, v35
	v_add_f32_e32 v39, v68, v35
	v_add_f32_e32 v36, v36, v37
	v_add_f32_e32 v37, v73, v35
	v_add_f32_e32 v38, v70, v35
	v_add_f32_e32 v39, v34, v39
	v_pk_add_f32 v[34:35], v[66:67], v[34:35]
	v_exp_f32_e32 v39, v39
	v_add_f32_e32 v34, v34, v35
	v_exp_f32_e32 v34, v34
	v_add_f32_e32 v38, v72, v38
	v_exp_f32_e32 v37, v37
	v_exp_f32_e32 v38, v38
	v_cndmask_b32_e64 v39, 0, v39, s[8:9]
	v_cndmask_b32_e32 v34, 0, v34, vcc
	v_cvt_pk_bf16_f32 v34, v34, v39
	v_cvt_pk_bf16_f32 v39, v49, v0
	v_add3_u32 v0, s79, v111, v112
	v_cndmask_b32_e64 v37, 0, v37, s[12:13]
	v_cndmask_b32_e64 v38, 0, v38, s[10:11]
	v_add3_u32 v0, v0, v113, v114
	v_add_f32_e32 v142, v142, v36
	v_cvt_pk_bf16_f32 v35, v38, v37
	v_cvt_pk_bf16_f32 v36, v45, v44
	v_cvt_pk_bf16_f32 v37, v43, v42
	ds_read_b64_tr_b16 v[42:43], v0
	ds_read_b64_tr_b16 v[44:45], v0 offset:512
	s_waitcnt lgkmcnt(0)
	v_mfma_f32_32x32x16_bf16 v[2:17], v[34:37], v[42:45], v[2:17]
	ds_read_b64_tr_b16 v[42:43], v0 offset:2048
	ds_read_b64_tr_b16 v[44:45], v0 offset:2560
	v_cvt_pk_bf16_f32 v38, v46, v148
	v_cvt_pk_bf16_f32 v41, v152, v147
	s_mov_b32 s8, 0xc2840000
	v_cmp_gt_f32_e32 vcc, s8, v142
	s_cmp_lg_u64 vcc, exec
	s_cselect_b64 s[8:9], -1, 0
	s_waitcnt lgkmcnt(0)
	v_mfma_f32_32x32x16_bf16 v[18:33], v[34:37], v[42:45], v[18:33]
	ds_read_b64_tr_b16 v[34:35], v0 offset:1024
	ds_read_b64_tr_b16 v[36:37], v0 offset:1536
	v_add_co_u32_e32 v143, vcc, -1, v143
	s_and_b64 s[8:9], vcc, s[8:9]
	s_addk_i32 s52, 0xf000
	s_sub_i32 s67, s67, 32
	s_and_b64 vcc, exec, s[8:9]
	s_waitcnt lgkmcnt(0)
	v_mfma_f32_32x32x16_bf16 v[2:17], v[38:41], v[34:37], v[2:17]
	ds_read_b64_tr_b16 v[34:35], v0 offset:3072
	ds_read_b64_tr_b16 v[36:37], v0 offset:3584
	s_waitcnt lgkmcnt(0)
	v_mfma_f32_32x32x16_bf16 v[18:33], v[38:41], v[34:37], v[18:33]
	s_cbranch_vccz .LBB9_554
